# k16 with packed f32 adds (v_pk_add_f32, one accumulator pair) for the softmax row sums in the MLA and L0 differential attention tile blocks: 17 instead of 34 adds per tile
# baseline (speedup 1.0000x reference)
; template <int DQK, int DV, int MODE, int QPRE, bool DIFF> ...
;     ...
; #pragma unroll
;                 for (int r = 0; r < 16; ++r) { s0[r] = __builtin_amdgcn_exp2f(s0[r]); s1[r] = __builtin_amdgcn_exp2f(s1[r]); ls = fadd_s(ls, fadd_s(s0[r], s1[r])); }
;                 l_run += ls;
;             } else {
;                 const bool diag = (t == my_last);
;                 const int qrel = q0 + wid * 32 + l32 - t * 64;
;                 float kp[32], gprod[8];
; #pragma unroll
;                 for (int k = 0; k < 8; ++k) {
; #pragma unroll
;                     for (int e = 0; e < 4; ++e) {
;                         const int r = (k & 3) * 4 + e;
;                         const float z2 = __builtin_amdgcn_fmed3f((k < 4) ? s0[r] : s1[r], -126.0f, 126.0f);
;                         const float E = __builtin_amdgcn_exp2f(z2);
;                         const float keep = __builtin_amdgcn_rcpf(fadd_s(E, 1.0f)), beta = fmul_s(E, keep);
;                         kp[k * 4 + e] = keep;
;                         if (k < 4) s0[r] = beta; else s1[r] = beta;
;                     }
;                 }
;                 if (diag) {
;                     asm volatile("" ::: "memory");
; #pragma unroll
;                     for (int k = 0; k < 8; ++k)
; #pragma unroll
;                         for (int e = 0; e < 4; ++e) { const int r = (k & 3) * 4 + e; const int kl = (k >> 2) * 32 + e + 8 * (k & 3) + 4 * hi; const bool valid = kl < qrel;
;                             kp[k * 4 + e] = valid ? kp[k * 4 + e] : 1.0f; if (k < 4) s0[r] = valid ? s0[r] : 0.f; else s1[r] = valid ? s1[r] : 0.f; }
;                 }
; #pragma unroll
;                 for (int k = 0; k < 8; ++k) gprod[k] = fmul_s(fmul_s(kp[k * 4], kp[k * 4 + 1]), fmul_s(kp[k * 4 + 2], kp[k * 4 + 3]));
;                 float base[8]; float suf = 1.0f;
; #pragma unroll
;                 for (int k = 7; k >= 0; --k) { float glo, ghi; swap32(gprod[k], glo, ghi); base[k] = fmul_s(fmul_s(Rp, suf), (hi == 0 ? ghi : 1.0f)); suf = fmul_s(suf, fmul_s(glo, ghi)); }
;                 Rp *= suf;
;                 { const bool nd = __all(Rp == 0.0f); if (nd && !sb_done && lane == 0) __hip_atomic_fetch_add(sbcnt, 1u, __ATOMIC_RELAXED, __HIP_MEMORY_SCOPE_WORKGROUP); sb_done = nd; }
; #pragma unroll
;                 for (int k = 0; k < 8; ++k) {
.Ldf_back0:
	v_exp_f32_e32 v80, v80
	v_exp_f32_e32 v81, v81
	v_exp_f32_e32 v82, v82
	v_exp_f32_e32 v83, v83
	v_exp_f32_e32 v84, v84
	v_pk_add_f32 v[236:237], v[80:81], v[82:83]
	v_exp_f32_e32 v85, v85
	v_exp_f32_e32 v86, v86
	v_pk_add_f32 v[236:237], v[236:237], v[84:85]
	v_exp_f32_e32 v87, v87
	s_nop 0
	v_pk_add_f32 v[236:237], v[236:237], v[86:87]
	v_cvt_pk_bf16_f32 v80, v80, v81
	v_cvt_pk_bf16_f32 v81, v82, v83
	v_cvt_pk_bf16_f32 v82, v84, v85
	v_cvt_pk_bf16_f32 v83, v86, v87
	v_exp_f32_e32 v88, v88
	v_exp_f32_e32 v89, v89
	v_exp_f32_e32 v90, v90
	v_pk_add_f32 v[236:237], v[236:237], v[88:89]
	v_exp_f32_e32 v91, v91
	v_exp_f32_e32 v92, v92
	v_pk_add_f32 v[236:237], v[236:237], v[90:91]
	v_exp_f32_e32 v93, v93
	v_exp_f32_e32 v94, v94
	v_pk_add_f32 v[236:237], v[236:237], v[92:93]
	v_exp_f32_e32 v95, v95
	s_nop 0
	v_pk_add_f32 v[236:237], v[236:237], v[94:95]
	v_cvt_pk_bf16_f32 v84, v88, v89
	v_cvt_pk_bf16_f32 v85, v90, v91
	v_cvt_pk_bf16_f32 v86, v92, v93
	v_cvt_pk_bf16_f32 v87, v94, v95
	v_exp_f32_e32 v96, v96
	v_exp_f32_e32 v97, v97
	v_exp_f32_e32 v98, v98
	v_pk_add_f32 v[236:237], v[236:237], v[96:97]
	v_exp_f32_e32 v99, v99
	v_exp_f32_e32 v100, v100
	v_pk_add_f32 v[236:237], v[236:237], v[98:99]
	v_exp_f32_e32 v101, v101
	v_exp_f32_e32 v102, v102
	v_pk_add_f32 v[236:237], v[236:237], v[100:101]
	v_exp_f32_e32 v103, v103
	s_nop 0
	v_pk_add_f32 v[236:237], v[236:237], v[102:103]
	v_cvt_pk_bf16_f32 v88, v96, v97
	v_cvt_pk_bf16_f32 v89, v98, v99
	v_cvt_pk_bf16_f32 v90, v100, v101
	v_cvt_pk_bf16_f32 v91, v102, v103
	v_exp_f32_e32 v104, v104
	v_exp_f32_e32 v105, v105
	v_exp_f32_e32 v106, v106
	v_pk_add_f32 v[236:237], v[236:237], v[104:105]
	v_exp_f32_e32 v107, v107
	v_exp_f32_e32 v108, v108
	v_pk_add_f32 v[236:237], v[236:237], v[106:107]
	v_exp_f32_e32 v109, v109
	v_exp_f32_e32 v110, v110
	v_pk_add_f32 v[236:237], v[236:237], v[108:109]
	v_exp_f32_e32 v111, v111
	s_nop 0
	v_pk_add_f32 v[236:237], v[236:237], v[110:111]
	v_cvt_pk_bf16_f32 v92, v104, v105
	v_cvt_pk_bf16_f32 v93, v106, v107
	v_cvt_pk_bf16_f32 v94, v108, v109
	v_cvt_pk_bf16_f32 v95, v110, v111
	v_add_f32_e32 v223, v236, v237
	v_add_f32_e32 v203, v203, v223
	s_waitcnt lgkmcnt(7)
	v_mfma_f32_32x32x16_bf16 v[48:63], v[240:243], v[80:83], v[48:63]
	ds_read_b128 v[168:171], v221 offset:9280
	s_waitcnt lgkmcnt(7)
	v_mfma_f32_32x32x16_bf16 v[32:47], v[244:247], v[80:83], v[32:47]
	ds_read_b128 v[172:175], v221 offset:13888
	s_waitcnt lgkmcnt(7)
	v_mfma_f32_32x32x16_bf16 v[0:15], v[248:251], v[80:83], v[0:15]
	ds_read_b128 v[176:179], v221 offset:18496
	s_waitcnt lgkmcnt(7)
	v_mfma_f32_32x32x16_bf16 v[16:31], v[148:151], v[80:83], v[16:31]
	ds_read_b128 v[240:243], v221 offset:23104
	s_waitcnt lgkmcnt(7)
	v_mfma_f32_32x32x16_bf16 v[48:63], v[152:155], v[84:87], v[48:63]
	ds_read_b128 v[244:247], v221 offset:9312
	s_waitcnt lgkmcnt(7)
	v_mfma_f32_32x32x16_bf16 v[32:47], v[156:159], v[84:87], v[32:47]
	ds_read_b128 v[248:251], v221 offset:13920
	s_waitcnt lgkmcnt(7)
	v_mfma_f32_32x32x16_bf16 v[0:15], v[160:163], v[84:87], v[0:15]
	ds_read_b128 v[148:151], v221 offset:18528
	s_waitcnt lgkmcnt(7)
	v_mfma_f32_32x32x16_bf16 v[16:31], v[164:167], v[84:87], v[16:31]
	ds_read_b128 v[152:155], v221 offset:23136
	s_waitcnt lgkmcnt(7)
	v_mfma_f32_32x32x16_bf16 v[48:63], v[168:171], v[88:91], v[48:63]
	s_waitcnt lgkmcnt(6)
	v_mfma_f32_32x32x16_bf16 v[32:47], v[172:175], v[88:91], v[32:47]
	s_waitcnt lgkmcnt(5)
	v_mfma_f32_32x32x16_bf16 v[0:15], v[176:179], v[88:91], v[0:15]
	s_waitcnt lgkmcnt(4)
	v_mfma_f32_32x32x16_bf16 v[16:31], v[240:243], v[88:91], v[16:31]
	s_waitcnt lgkmcnt(3)
	v_mfma_f32_32x32x16_bf16 v[48:63], v[244:247], v[92:95], v[48:63]
	s_waitcnt lgkmcnt(2)
	v_mfma_f32_32x32x16_bf16 v[32:47], v[248:251], v[92:95], v[32:47]
	s_waitcnt lgkmcnt(1)
	v_mfma_f32_32x32x16_bf16 v[0:15], v[148:151], v[92:95], v[0:15]
	s_waitcnt lgkmcnt(0)
	v_mfma_f32_32x32x16_bf16 v[16:31], v[152:155], v[92:95], v[16:31]
	s_cmp_ge_u32 s6, s31
	s_cbranch_scc1 .LBB0_570

; template <int DQK, int DV, int MODE, int QPRE, bool DIFF> ...
;     ...
; #pragma unroll
;                 for (int r = 0; r < 16; ++r) { s0[r] = __builtin_amdgcn_exp2f(s0[r]); s1[r] = __builtin_amdgcn_exp2f(s1[r]); ls = fadd_s(ls, fadd_s(s0[r], s1[r])); }
;                 l_run += ls;
;             } else {
;                 const bool diag = (t == my_last);
;                 const int qrel = q0 + wid * 32 + l32 - t * 64;
;                 float kp[32], gprod[8];
; #pragma unroll
;                 for (int k = 0; k < 8; ++k) {
; #pragma unroll
;                     for (int e = 0; e < 4; ++e) {
;                         const int r = (k & 3) * 4 + e;
;                         const float z2 = __builtin_amdgcn_fmed3f((k < 4) ? s0[r] : s1[r], -126.0f, 126.0f);
;                         const float E = __builtin_amdgcn_exp2f(z2);
;                         const float keep = __builtin_amdgcn_rcpf(fadd_s(E, 1.0f)), beta = fmul_s(E, keep);
;                         kp[k * 4 + e] = keep;
;                         if (k < 4) s0[r] = beta; else s1[r] = beta;
;                     }
;                 }
;                 if (diag) {
;                     asm volatile("" ::: "memory");
; #pragma unroll
;                     for (int k = 0; k < 8; ++k)
; #pragma unroll
;                         for (int e = 0; e < 4; ++e) { const int r = (k & 3) * 4 + e; const int kl = (k >> 2) * 32 + e + 8 * (k & 3) + 4 * hi; const bool valid = kl < qrel;
;                             kp[k * 4 + e] = valid ? kp[k * 4 + e] : 1.0f; if (k < 4) s0[r] = valid ? s0[r] : 0.f; else s1[r] = valid ? s1[r] : 0.f; }
;                 }
; #pragma unroll
;                 for (int k = 0; k < 8; ++k) gprod[k] = fmul_s(fmul_s(kp[k * 4], kp[k * 4 + 1]), fmul_s(kp[k * 4 + 2], kp[k * 4 + 3]));
;                 float base[8]; float suf = 1.0f;
; #pragma unroll
;                 for (int k = 7; k >= 0; --k) { float glo, ghi; swap32(gprod[k], glo, ghi); base[k] = fmul_s(fmul_s(Rp, suf), (hi == 0 ? ghi : 1.0f)); suf = fmul_s(suf, fmul_s(glo, ghi)); }
;                 Rp *= suf;
;                 { const bool nd = __all(Rp == 0.0f); if (nd && !sb_done && lane == 0) __hip_atomic_fetch_add(sbcnt, 1u, __ATOMIC_RELAXED, __HIP_MEMORY_SCOPE_WORKGROUP); sb_done = nd; }
; #pragma unroll
;                 for (int k = 0; k < 8; ++k) {
.Lmla_back0a:
	v_exp_f32_e32 v48, v48
	v_exp_f32_e32 v49, v49
	v_exp_f32_e32 v50, v50
	v_exp_f32_e32 v51, v51
	v_exp_f32_e32 v52, v52
	v_pk_add_f32 v[252:253], v[48:49], v[50:51]
	v_exp_f32_e32 v53, v53
	v_exp_f32_e32 v54, v54
	v_pk_add_f32 v[252:253], v[252:253], v[52:53]
	v_exp_f32_e32 v55, v55
	s_nop 0
	v_pk_add_f32 v[252:253], v[252:253], v[54:55]
	v_cvt_pk_bf16_f32 v48, v48, v49
	v_cvt_pk_bf16_f32 v49, v50, v51
	v_cvt_pk_bf16_f32 v50, v52, v53
	v_cvt_pk_bf16_f32 v51, v54, v55
	v_exp_f32_e32 v56, v56
	v_exp_f32_e32 v57, v57
	v_exp_f32_e32 v58, v58
	v_pk_add_f32 v[252:253], v[252:253], v[56:57]
	v_exp_f32_e32 v59, v59
	v_exp_f32_e32 v60, v60
	v_pk_add_f32 v[252:253], v[252:253], v[58:59]
	v_exp_f32_e32 v61, v61
	v_exp_f32_e32 v62, v62
	v_pk_add_f32 v[252:253], v[252:253], v[60:61]
	v_exp_f32_e32 v63, v63
	s_nop 0
	v_pk_add_f32 v[252:253], v[252:253], v[62:63]
	v_cvt_pk_bf16_f32 v52, v56, v57
	v_cvt_pk_bf16_f32 v53, v58, v59
	v_cvt_pk_bf16_f32 v54, v60, v61
	v_cvt_pk_bf16_f32 v55, v62, v63
	v_exp_f32_e32 v64, v64
	v_exp_f32_e32 v65, v65
	v_exp_f32_e32 v66, v66
	v_pk_add_f32 v[252:253], v[252:253], v[64:65]
	v_exp_f32_e32 v67, v67
	v_exp_f32_e32 v68, v68
	v_pk_add_f32 v[252:253], v[252:253], v[66:67]
	v_exp_f32_e32 v69, v69
	v_exp_f32_e32 v70, v70
	v_pk_add_f32 v[252:253], v[252:253], v[68:69]
	v_exp_f32_e32 v71, v71
	s_nop 0
	v_pk_add_f32 v[252:253], v[252:253], v[70:71]
	v_cvt_pk_bf16_f32 v56, v64, v65
	v_cvt_pk_bf16_f32 v57, v66, v67
	v_cvt_pk_bf16_f32 v58, v68, v69
	v_cvt_pk_bf16_f32 v59, v70, v71
	v_exp_f32_e32 v72, v72
	v_exp_f32_e32 v73, v73
	v_exp_f32_e32 v74, v74
	v_pk_add_f32 v[252:253], v[252:253], v[72:73]
	v_exp_f32_e32 v75, v75
	v_exp_f32_e32 v76, v76
	v_pk_add_f32 v[252:253], v[252:253], v[74:75]
	v_exp_f32_e32 v77, v77
	v_exp_f32_e32 v78, v78
	v_pk_add_f32 v[252:253], v[252:253], v[76:77]
	v_exp_f32_e32 v79, v79
	s_nop 0
	v_pk_add_f32 v[252:253], v[252:253], v[78:79]
	v_cvt_pk_bf16_f32 v60, v72, v73
	v_cvt_pk_bf16_f32 v61, v74, v75
	v_cvt_pk_bf16_f32 v62, v76, v77
	v_cvt_pk_bf16_f32 v63, v78, v79
	v_add_f32_e32 v252, v252, v253
	v_add_f32_e32 v196, v196, v252
	s_waitcnt lgkmcnt(5)
	v_mfma_f32_32x32x16_bf16 v[16:31], v[236:239], v[48:51], v[16:31]
	ds_read_b128 v[160:163], v198 offset:13408
	s_waitcnt lgkmcnt(5)
	v_mfma_f32_32x32x16_bf16 v[0:15], v[240:243], v[48:51], v[0:15]
	ds_read_b128 v[164:167], v198 offset:18016
	s_waitcnt lgkmcnt(5)
	v_mfma_f32_32x32x16_bf16 v[16:31], v[244:247], v[52:55], v[16:31]
	ds_read_b128 v[236:239], v195 offset:22528
	s_waitcnt lgkmcnt(5)
	v_mfma_f32_32x32x16_bf16 v[0:15], v[248:251], v[52:55], v[0:15]
	ds_read_b128 v[240:243], v195 offset:29184
	s_waitcnt lgkmcnt(5)
	v_mfma_f32_32x32x16_bf16 v[16:31], v[152:155], v[56:59], v[16:31]
	ds_read_b128 v[244:247], v195 offset:22560
	s_waitcnt lgkmcnt(5)
	v_mfma_f32_32x32x16_bf16 v[0:15], v[156:159], v[56:59], v[0:15]
	ds_read_b128 v[248:251], v195 offset:29216
	s_waitcnt lgkmcnt(5)
	v_mfma_f32_32x32x16_bf16 v[16:31], v[160:163], v[60:63], v[16:31]
	ds_read_b128 v[152:155], v195 offset:22592
	s_waitcnt lgkmcnt(5)
	v_mfma_f32_32x32x16_bf16 v[0:15], v[164:167], v[60:63], v[0:15]
	ds_read_b128 v[156:159], v195 offset:29248
	s_waitcnt lgkmcnt(5)
	v_mfma_f32_32x32x16_bf16 v[204:219], v[236:239], v[128:131], v[32:47]
	ds_read_b128 v[160:163], v195 offset:22624
	s_waitcnt lgkmcnt(5)
	v_mfma_f32_32x32x16_bf16 v[220:235], v[240:243], v[128:131], v[32:47]
	ds_read_b128 v[164:167], v195 offset:29280
	s_waitcnt lgkmcnt(5)
	v_mfma_f32_32x32x16_bf16 v[204:219], v[244:247], v[132:135], v[204:219]
	ds_read_b128 v[236:239], v195 offset:22656
	s_waitcnt lgkmcnt(5)
	v_mfma_f32_32x32x16_bf16 v[220:235], v[248:251], v[132:135], v[220:235]
	ds_read_b128 v[240:243], v195 offset:29312
	s_waitcnt lgkmcnt(5)
	v_mfma_f32_32x32x16_bf16 v[204:219], v[152:155], v[136:139], v[204:219]
	ds_read_b128 v[244:247], v195 offset:22688
	s_waitcnt lgkmcnt(5)
	v_mfma_f32_32x32x16_bf16 v[220:235], v[156:159], v[136:139], v[220:235]
	ds_read_b128 v[248:251], v195 offset:29344
	s_waitcnt lgkmcnt(5)
	v_mfma_f32_32x32x16_bf16 v[204:219], v[160:163], v[140:143], v[204:219]
	ds_read_b128 v[152:155], v198 offset:35840
	s_waitcnt lgkmcnt(5)
	v_mfma_f32_32x32x16_bf16 v[220:235], v[164:167], v[140:143], v[220:235]
	ds_read_b128 v[156:159], v198 offset:40448
	s_waitcnt lgkmcnt(5)
	v_mfma_f32_32x32x16_bf16 v[204:219], v[236:239], v[144:147], v[204:219]
	ds_read_b128 v[160:163], v198 offset:35872
	s_waitcnt lgkmcnt(5)
	v_mfma_f32_32x32x16_bf16 v[220:235], v[240:243], v[144:147], v[220:235]
	ds_read_b128 v[164:167], v198 offset:40480
	s_waitcnt lgkmcnt(5)
	v_mfma_f32_32x32x16_bf16 v[204:219], v[244:247], v[148:151], v[204:219]
	ds_read_b128 v[236:239], v198 offset:35904
	s_waitcnt lgkmcnt(5)
	v_mfma_f32_32x32x16_bf16 v[220:235], v[248:251], v[148:151], v[220:235]
	ds_read_b128 v[240:243], v198 offset:40512
	s_nop 7
	v_max3_f32 v199, v204, v205, v206
	s_nop 1
	v_max3_f32 v252, v220, v221, v222
	v_max3_f32 v199, v199, v207, v208
	v_max3_f32 v252, v252, v223, v224
	v_max3_f32 v199, v199, v209, v210
	v_max3_f32 v252, v252, v225, v226
	v_max3_f32 v199, v199, v211, v212
	v_max3_f32 v252, v252, v227, v228
	v_max3_f32 v199, v199, v213, v214
	v_max3_f32 v252, v252, v229, v230
	v_max3_f32 v199, v199, v215, v216
	v_max3_f32 v252, v252, v231, v232
	v_max3_f32 v199, v199, v217, v218
	v_max3_f32 v252, v252, v233, v234
	v_max3_f32 v199, v199, v219, v235
	v_max_f32_e32 v199, v199, v252
	v_mov_b32_e32 v252, v199
	s_nop 1
	v_permlane32_swap_b32_e32 v199, v252
	v_max_f32_e32 v199, v199, v252
	v_cmp_lt_f32_e32 vcc, s51, v199
	s_cbranch_vccnz .Lmla_rare0b
; template <int DQK, int DV, int MODE, int QPRE, bool DIFF> ...
;     ...
; #pragma unroll
;                 for (int r = 0; r < 16; ++r) { s0[r] = __builtin_amdgcn_exp2f(s0[r]); s1[r] = __builtin_amdgcn_exp2f(s1[r]); ls = fadd_s(ls, fadd_s(s0[r], s1[r])); }
;                 l_run += ls;
;             } else {
;                 const bool diag = (t == my_last);
;                 const int qrel = q0 + wid * 32 + l32 - t * 64;
;                 float kp[32], gprod[8];
; #pragma unroll
;                 for (int k = 0; k < 8; ++k) {
; #pragma unroll
;                     for (int e = 0; e < 4; ++e) {
;                         const int r = (k & 3) * 4 + e;
;                         const float z2 = __builtin_amdgcn_fmed3f((k < 4) ? s0[r] : s1[r], -126.0f, 126.0f);
;                         const float E = __builtin_amdgcn_exp2f(z2);
;                         const float keep = __builtin_amdgcn_rcpf(fadd_s(E, 1.0f)), beta = fmul_s(E, keep);
;                         kp[k * 4 + e] = keep;
;                         if (k < 4) s0[r] = beta; else s1[r] = beta;
;                     }
;                 }
;                 if (diag) {
;                     asm volatile("" ::: "memory");
; #pragma unroll
;                     for (int k = 0; k < 8; ++k)
; #pragma unroll
;                         for (int e = 0; e < 4; ++e) { const int r = (k & 3) * 4 + e; const int kl = (k >> 2) * 32 + e + 8 * (k & 3) + 4 * hi; const bool valid = kl < qrel;
;                             kp[k * 4 + e] = valid ? kp[k * 4 + e] : 1.0f; if (k < 4) s0[r] = valid ? s0[r] : 0.f; else s1[r] = valid ? s1[r] : 0.f; }
;                 }
; #pragma unroll
;                 for (int k = 0; k < 8; ++k) gprod[k] = fmul_s(fmul_s(kp[k * 4], kp[k * 4 + 1]), fmul_s(kp[k * 4 + 2], kp[k * 4 + 3]));
;                 float base[8]; float suf = 1.0f;
; #pragma unroll
;                 for (int k = 7; k >= 0; --k) { float glo, ghi; swap32(gprod[k], glo, ghi); base[k] = fmul_s(fmul_s(Rp, suf), (hi == 0 ? ghi : 1.0f)); suf = fmul_s(suf, fmul_s(glo, ghi)); }
;                 Rp *= suf;
;                 { const bool nd = __all(Rp == 0.0f); if (nd && !sb_done && lane == 0) __hip_atomic_fetch_add(sbcnt, 1u, __ATOMIC_RELAXED, __HIP_MEMORY_SCOPE_WORKGROUP); sb_done = nd; }
; #pragma unroll
;                 for (int k = 0; k < 8; ++k) {
.Lmla_back0b:
	v_exp_f32_e32 v204, v204
	v_exp_f32_e32 v205, v205
	v_exp_f32_e32 v206, v206
	v_exp_f32_e32 v207, v207
	v_exp_f32_e32 v208, v208
	v_pk_add_f32 v[252:253], v[204:205], v[206:207]
	v_exp_f32_e32 v209, v209
	v_exp_f32_e32 v210, v210
	v_pk_add_f32 v[252:253], v[252:253], v[208:209]
	v_exp_f32_e32 v211, v211
	s_nop 0
	v_pk_add_f32 v[252:253], v[252:253], v[210:211]
	v_cvt_pk_bf16_f32 v204, v204, v205
	v_cvt_pk_bf16_f32 v205, v206, v207
	v_cvt_pk_bf16_f32 v206, v208, v209
	v_cvt_pk_bf16_f32 v207, v210, v211
	v_exp_f32_e32 v212, v212
	v_exp_f32_e32 v213, v213
	v_exp_f32_e32 v214, v214
	v_pk_add_f32 v[252:253], v[252:253], v[212:213]
	v_exp_f32_e32 v215, v215
	v_exp_f32_e32 v216, v216
	v_pk_add_f32 v[252:253], v[252:253], v[214:215]
	v_exp_f32_e32 v217, v217
	v_exp_f32_e32 v218, v218
	v_pk_add_f32 v[252:253], v[252:253], v[216:217]
	v_exp_f32_e32 v219, v219
	s_nop 0
	v_pk_add_f32 v[252:253], v[252:253], v[218:219]
	v_cvt_pk_bf16_f32 v208, v212, v213
	v_cvt_pk_bf16_f32 v209, v214, v215
	v_cvt_pk_bf16_f32 v210, v216, v217
	v_cvt_pk_bf16_f32 v211, v218, v219
	v_exp_f32_e32 v220, v220
	v_exp_f32_e32 v221, v221
	v_exp_f32_e32 v222, v222
	v_pk_add_f32 v[252:253], v[252:253], v[220:221]
	v_exp_f32_e32 v223, v223
	v_exp_f32_e32 v224, v224
	v_pk_add_f32 v[252:253], v[252:253], v[222:223]
	v_exp_f32_e32 v225, v225
	v_exp_f32_e32 v226, v226
	v_pk_add_f32 v[252:253], v[252:253], v[224:225]
	v_exp_f32_e32 v227, v227
	s_nop 0
	v_pk_add_f32 v[252:253], v[252:253], v[226:227]
	v_cvt_pk_bf16_f32 v212, v220, v221
	v_cvt_pk_bf16_f32 v213, v222, v223
	v_cvt_pk_bf16_f32 v214, v224, v225
	v_cvt_pk_bf16_f32 v215, v226, v227
	v_exp_f32_e32 v228, v228
	v_exp_f32_e32 v229, v229
	v_exp_f32_e32 v230, v230
	v_pk_add_f32 v[252:253], v[252:253], v[228:229]
	v_exp_f32_e32 v231, v231
	v_exp_f32_e32 v232, v232
	v_pk_add_f32 v[252:253], v[252:253], v[230:231]
	v_exp_f32_e32 v233, v233
	v_exp_f32_e32 v234, v234
	v_pk_add_f32 v[252:253], v[252:253], v[232:233]
	v_exp_f32_e32 v235, v235
	s_nop 0
	v_pk_add_f32 v[252:253], v[252:253], v[234:235]
	v_cvt_pk_bf16_f32 v216, v228, v229
	v_cvt_pk_bf16_f32 v217, v230, v231
	v_cvt_pk_bf16_f32 v218, v232, v233
	v_cvt_pk_bf16_f32 v219, v234, v235
	v_add_f32_e32 v252, v252, v253
	v_add_f32_e32 v196, v196, v252
	s_waitcnt lgkmcnt(5)
	v_mfma_f32_32x32x16_bf16 v[16:31], v[152:155], v[204:207], v[16:31]
	ds_read_b128 v[244:247], v198 offset:35936
	s_waitcnt lgkmcnt(5)
	v_mfma_f32_32x32x16_bf16 v[0:15], v[156:159], v[204:207], v[0:15]
	ds_read_b128 v[248:251], v198 offset:40544
	s_waitcnt lgkmcnt(5)
	v_mfma_f32_32x32x16_bf16 v[16:31], v[160:163], v[208:211], v[16:31]
	s_waitcnt lgkmcnt(4)
	v_mfma_f32_32x32x16_bf16 v[0:15], v[164:167], v[208:211], v[0:15]
	s_waitcnt lgkmcnt(3)
	v_mfma_f32_32x32x16_bf16 v[16:31], v[236:239], v[212:215], v[16:31]
	s_waitcnt lgkmcnt(2)
	v_mfma_f32_32x32x16_bf16 v[0:15], v[240:243], v[212:215], v[0:15]
	s_waitcnt lgkmcnt(1)
	v_mfma_f32_32x32x16_bf16 v[16:31], v[244:247], v[216:219], v[16:31]
	s_waitcnt lgkmcnt(0)
	v_mfma_f32_32x32x16_bf16 v[0:15], v[248:251], v[216:219], v[0:15]
	s_branch .LBB0_1667

; template <int DQK, int DV, int MODE, int QPRE, bool DIFF> ...
;     ...
; #pragma unroll
;                 for (int r = 0; r < 16; ++r) { s0[r] = __builtin_amdgcn_exp2f(s0[r]); s1[r] = __builtin_amdgcn_exp2f(s1[r]); ls = fadd_s(ls, fadd_s(s0[r], s1[r])); }
;                 l_run += ls;
;             } else {
;                 const bool diag = (t == my_last);
;                 const int qrel = q0 + wid * 32 + l32 - t * 64;
;                 float kp[32], gprod[8];
; #pragma unroll
;                 for (int k = 0; k < 8; ++k) {
; #pragma unroll
;                     for (int e = 0; e < 4; ++e) {
;                         const int r = (k & 3) * 4 + e;
;                         const float z2 = __builtin_amdgcn_fmed3f((k < 4) ? s0[r] : s1[r], -126.0f, 126.0f);
;                         const float E = __builtin_amdgcn_exp2f(z2);
;                         const float keep = __builtin_amdgcn_rcpf(fadd_s(E, 1.0f)), beta = fmul_s(E, keep);
;                         kp[k * 4 + e] = keep;
;                         if (k < 4) s0[r] = beta; else s1[r] = beta;
;                     }
;                 }
;                 if (diag) {
;                     asm volatile("" ::: "memory");
; #pragma unroll
;                     for (int k = 0; k < 8; ++k)
; #pragma unroll
;                         for (int e = 0; e < 4; ++e) { const int r = (k & 3) * 4 + e; const int kl = (k >> 2) * 32 + e + 8 * (k & 3) + 4 * hi; const bool valid = kl < qrel;
;                             kp[k * 4 + e] = valid ? kp[k * 4 + e] : 1.0f; if (k < 4) s0[r] = valid ? s0[r] : 0.f; else s1[r] = valid ? s1[r] : 0.f; }
;                 }
; #pragma unroll
;                 for (int k = 0; k < 8; ++k) gprod[k] = fmul_s(fmul_s(kp[k * 4], kp[k * 4 + 1]), fmul_s(kp[k * 4 + 2], kp[k * 4 + 3]));
;                 float base[8]; float suf = 1.0f;
; #pragma unroll
;                 for (int k = 7; k >= 0; --k) { float glo, ghi; swap32(gprod[k], glo, ghi); base[k] = fmul_s(fmul_s(Rp, suf), (hi == 0 ? ghi : 1.0f)); suf = fmul_s(suf, fmul_s(glo, ghi)); }
;                 Rp *= suf;
;                 { const bool nd = __all(Rp == 0.0f); if (nd && !sb_done && lane == 0) __hip_atomic_fetch_add(sbcnt, 1u, __ATOMIC_RELAXED, __HIP_MEMORY_SCOPE_WORKGROUP); sb_done = nd; }
; #pragma unroll
;                 for (int k = 0; k < 8; ++k) {
.Lmla_back1a:
	v_exp_f32_e32 v48, v48
	v_exp_f32_e32 v49, v49
	v_exp_f32_e32 v50, v50
	v_exp_f32_e32 v51, v51
	v_exp_f32_e32 v52, v52
	v_pk_add_f32 v[252:253], v[48:49], v[50:51]
	v_exp_f32_e32 v53, v53
	v_exp_f32_e32 v54, v54
	v_pk_add_f32 v[252:253], v[252:253], v[52:53]
	v_exp_f32_e32 v55, v55
	s_nop 0
	v_pk_add_f32 v[252:253], v[252:253], v[54:55]
	v_cvt_pk_bf16_f32 v48, v48, v49
	v_cvt_pk_bf16_f32 v49, v50, v51
	v_cvt_pk_bf16_f32 v50, v52, v53
	v_cvt_pk_bf16_f32 v51, v54, v55
	v_exp_f32_e32 v56, v56
	v_exp_f32_e32 v57, v57
	v_exp_f32_e32 v58, v58
	v_pk_add_f32 v[252:253], v[252:253], v[56:57]
	v_exp_f32_e32 v59, v59
	v_exp_f32_e32 v60, v60
	v_pk_add_f32 v[252:253], v[252:253], v[58:59]
	v_exp_f32_e32 v61, v61
	v_exp_f32_e32 v62, v62
	v_pk_add_f32 v[252:253], v[252:253], v[60:61]
	v_exp_f32_e32 v63, v63
	s_nop 0
	v_pk_add_f32 v[252:253], v[252:253], v[62:63]
	v_cvt_pk_bf16_f32 v52, v56, v57
	v_cvt_pk_bf16_f32 v53, v58, v59
	v_cvt_pk_bf16_f32 v54, v60, v61
	v_cvt_pk_bf16_f32 v55, v62, v63
	v_exp_f32_e32 v64, v64
	v_exp_f32_e32 v65, v65
	v_exp_f32_e32 v66, v66
	v_pk_add_f32 v[252:253], v[252:253], v[64:65]
	v_exp_f32_e32 v67, v67
	v_exp_f32_e32 v68, v68
	v_pk_add_f32 v[252:253], v[252:253], v[66:67]
	v_exp_f32_e32 v69, v69
	v_exp_f32_e32 v70, v70
	v_pk_add_f32 v[252:253], v[252:253], v[68:69]
	v_exp_f32_e32 v71, v71
	s_nop 0
	v_pk_add_f32 v[252:253], v[252:253], v[70:71]
	v_cvt_pk_bf16_f32 v56, v64, v65
	v_cvt_pk_bf16_f32 v57, v66, v67
	v_cvt_pk_bf16_f32 v58, v68, v69
	v_cvt_pk_bf16_f32 v59, v70, v71
	v_exp_f32_e32 v72, v72
	v_exp_f32_e32 v73, v73
	v_exp_f32_e32 v74, v74
	v_pk_add_f32 v[252:253], v[252:253], v[72:73]
	v_exp_f32_e32 v75, v75
	v_exp_f32_e32 v76, v76
	v_pk_add_f32 v[252:253], v[252:253], v[74:75]
	v_exp_f32_e32 v77, v77
	v_exp_f32_e32 v78, v78
	v_pk_add_f32 v[252:253], v[252:253], v[76:77]
	v_exp_f32_e32 v79, v79
	s_nop 0
	v_pk_add_f32 v[252:253], v[252:253], v[78:79]
	v_cvt_pk_bf16_f32 v60, v72, v73
	v_cvt_pk_bf16_f32 v61, v74, v75
	v_cvt_pk_bf16_f32 v62, v76, v77
	v_cvt_pk_bf16_f32 v63, v78, v79
	v_add_f32_e32 v252, v252, v253
	v_add_f32_e32 v196, v196, v252
	s_waitcnt lgkmcnt(5)
	v_mfma_f32_32x32x16_bf16 v[16:31], v[236:239], v[48:51], v[16:31]
	ds_read_b128 v[160:163], v198 offset:58464
	s_waitcnt lgkmcnt(5)
	v_mfma_f32_32x32x16_bf16 v[0:15], v[240:243], v[48:51], v[0:15]
	ds_read_b128 v[164:167], v198 offset:63072
	s_waitcnt lgkmcnt(5)
	v_mfma_f32_32x32x16_bf16 v[16:31], v[244:247], v[52:55], v[16:31]
	ds_read_b128 v[236:239], v194
	s_waitcnt lgkmcnt(5)
	v_mfma_f32_32x32x16_bf16 v[0:15], v[248:251], v[52:55], v[0:15]
	ds_read_b128 v[240:243], v194 offset:6656
	s_waitcnt lgkmcnt(5)
	v_mfma_f32_32x32x16_bf16 v[16:31], v[152:155], v[56:59], v[16:31]
	ds_read_b128 v[244:247], v194 offset:32
	s_waitcnt lgkmcnt(5)
	v_mfma_f32_32x32x16_bf16 v[0:15], v[156:159], v[56:59], v[0:15]
	ds_read_b128 v[248:251], v194 offset:6688
	s_waitcnt lgkmcnt(5)
	v_mfma_f32_32x32x16_bf16 v[16:31], v[160:163], v[60:63], v[16:31]
	ds_read_b128 v[152:155], v194 offset:64
	s_waitcnt lgkmcnt(5)
	v_mfma_f32_32x32x16_bf16 v[0:15], v[164:167], v[60:63], v[0:15]
	ds_read_b128 v[156:159], v194 offset:6720
	s_waitcnt lgkmcnt(5)
	v_mfma_f32_32x32x16_bf16 v[204:219], v[236:239], v[128:131], v[32:47]
	ds_read_b128 v[160:163], v194 offset:96
	s_waitcnt lgkmcnt(5)
	v_mfma_f32_32x32x16_bf16 v[220:235], v[240:243], v[128:131], v[32:47]
	ds_read_b128 v[164:167], v194 offset:6752
	s_waitcnt lgkmcnt(5)
	v_mfma_f32_32x32x16_bf16 v[204:219], v[244:247], v[132:135], v[204:219]
	ds_read_b128 v[236:239], v194 offset:128
	s_waitcnt lgkmcnt(5)
	v_mfma_f32_32x32x16_bf16 v[220:235], v[248:251], v[132:135], v[220:235]
	ds_read_b128 v[240:243], v194 offset:6784
	s_waitcnt lgkmcnt(5)
	v_mfma_f32_32x32x16_bf16 v[204:219], v[152:155], v[136:139], v[204:219]
	ds_read_b128 v[244:247], v194 offset:160
	s_waitcnt lgkmcnt(5)
	v_mfma_f32_32x32x16_bf16 v[220:235], v[156:159], v[136:139], v[220:235]
	ds_read_b128 v[248:251], v194 offset:6816
	s_waitcnt lgkmcnt(5)
	v_mfma_f32_32x32x16_bf16 v[204:219], v[160:163], v[140:143], v[204:219]
	ds_read_b128 v[152:155], v197
	s_waitcnt lgkmcnt(5)
	v_mfma_f32_32x32x16_bf16 v[220:235], v[164:167], v[140:143], v[220:235]
	ds_read_b128 v[156:159], v197 offset:4608
	s_waitcnt lgkmcnt(5)
	v_mfma_f32_32x32x16_bf16 v[204:219], v[236:239], v[144:147], v[204:219]
	ds_read_b128 v[160:163], v197 offset:32
	s_waitcnt lgkmcnt(5)
	v_mfma_f32_32x32x16_bf16 v[220:235], v[240:243], v[144:147], v[220:235]
	ds_read_b128 v[164:167], v197 offset:4640
	s_waitcnt lgkmcnt(5)
	v_mfma_f32_32x32x16_bf16 v[204:219], v[244:247], v[148:151], v[204:219]
	ds_read_b128 v[236:239], v197 offset:64
	s_waitcnt lgkmcnt(5)
	v_mfma_f32_32x32x16_bf16 v[220:235], v[248:251], v[148:151], v[220:235]
	ds_read_b128 v[240:243], v197 offset:4672
	s_nop 7
	v_max3_f32 v199, v204, v205, v206
	s_nop 1
	v_max3_f32 v252, v220, v221, v222
	v_max3_f32 v199, v199, v207, v208
	v_max3_f32 v252, v252, v223, v224
	v_max3_f32 v199, v199, v209, v210
	v_max3_f32 v252, v252, v225, v226
	v_max3_f32 v199, v199, v211, v212
	v_max3_f32 v252, v252, v227, v228
	v_max3_f32 v199, v199, v213, v214
	v_max3_f32 v252, v252, v229, v230
	v_max3_f32 v199, v199, v215, v216
	v_max3_f32 v252, v252, v231, v232
	v_max3_f32 v199, v199, v217, v218
	v_max3_f32 v252, v252, v233, v234
	v_max3_f32 v199, v199, v219, v235
	v_max_f32_e32 v199, v199, v252
	v_mov_b32_e32 v252, v199
	s_nop 1
	v_permlane32_swap_b32_e32 v199, v252
	v_max_f32_e32 v199, v199, v252
	v_cmp_lt_f32_e32 vcc, s51, v199
	s_cbranch_vccnz .Lmla_rare1b
; template <int DQK, int DV, int MODE, int QPRE, bool DIFF> ...
;     ...
; #pragma unroll
;                 for (int r = 0; r < 16; ++r) { s0[r] = __builtin_amdgcn_exp2f(s0[r]); s1[r] = __builtin_amdgcn_exp2f(s1[r]); ls = fadd_s(ls, fadd_s(s0[r], s1[r])); }
;                 l_run += ls;
;             } else {
;                 const bool diag = (t == my_last);
;                 const int qrel = q0 + wid * 32 + l32 - t * 64;
;                 float kp[32], gprod[8];
; #pragma unroll
;                 for (int k = 0; k < 8; ++k) {
; #pragma unroll
;                     for (int e = 0; e < 4; ++e) {
;                         const int r = (k & 3) * 4 + e;
;                         const float z2 = __builtin_amdgcn_fmed3f((k < 4) ? s0[r] : s1[r], -126.0f, 126.0f);
;                         const float E = __builtin_amdgcn_exp2f(z2);
;                         const float keep = __builtin_amdgcn_rcpf(fadd_s(E, 1.0f)), beta = fmul_s(E, keep);
;                         kp[k * 4 + e] = keep;
;                         if (k < 4) s0[r] = beta; else s1[r] = beta;
;                     }
;                 }
;                 if (diag) {
;                     asm volatile("" ::: "memory");
; #pragma unroll
;                     for (int k = 0; k < 8; ++k)
; #pragma unroll
;                         for (int e = 0; e < 4; ++e) { const int r = (k & 3) * 4 + e; const int kl = (k >> 2) * 32 + e + 8 * (k & 3) + 4 * hi; const bool valid = kl < qrel;
;                             kp[k * 4 + e] = valid ? kp[k * 4 + e] : 1.0f; if (k < 4) s0[r] = valid ? s0[r] : 0.f; else s1[r] = valid ? s1[r] : 0.f; }
;                 }
; #pragma unroll
;                 for (int k = 0; k < 8; ++k) gprod[k] = fmul_s(fmul_s(kp[k * 4], kp[k * 4 + 1]), fmul_s(kp[k * 4 + 2], kp[k * 4 + 3]));
;                 float base[8]; float suf = 1.0f;
; #pragma unroll
;                 for (int k = 7; k >= 0; --k) { float glo, ghi; swap32(gprod[k], glo, ghi); base[k] = fmul_s(fmul_s(Rp, suf), (hi == 0 ? ghi : 1.0f)); suf = fmul_s(suf, fmul_s(glo, ghi)); }
;                 Rp *= suf;
;                 { const bool nd = __all(Rp == 0.0f); if (nd && !sb_done && lane == 0) __hip_atomic_fetch_add(sbcnt, 1u, __ATOMIC_RELAXED, __HIP_MEMORY_SCOPE_WORKGROUP); sb_done = nd; }
; #pragma unroll
;                 for (int k = 0; k < 8; ++k) {
.Lmla_back1b:
	v_exp_f32_e32 v204, v204
	v_exp_f32_e32 v205, v205
	v_exp_f32_e32 v206, v206
	v_exp_f32_e32 v207, v207
	v_exp_f32_e32 v208, v208
	v_pk_add_f32 v[252:253], v[204:205], v[206:207]
	v_exp_f32_e32 v209, v209
	v_exp_f32_e32 v210, v210
	v_pk_add_f32 v[252:253], v[252:253], v[208:209]
	v_exp_f32_e32 v211, v211
	s_nop 0
	v_pk_add_f32 v[252:253], v[252:253], v[210:211]
	v_cvt_pk_bf16_f32 v204, v204, v205
	v_cvt_pk_bf16_f32 v205, v206, v207
	v_cvt_pk_bf16_f32 v206, v208, v209
	v_cvt_pk_bf16_f32 v207, v210, v211
	v_exp_f32_e32 v212, v212
	v_exp_f32_e32 v213, v213
	v_exp_f32_e32 v214, v214
	v_pk_add_f32 v[252:253], v[252:253], v[212:213]
	v_exp_f32_e32 v215, v215
	v_exp_f32_e32 v216, v216
	v_pk_add_f32 v[252:253], v[252:253], v[214:215]
	v_exp_f32_e32 v217, v217
	v_exp_f32_e32 v218, v218
	v_pk_add_f32 v[252:253], v[252:253], v[216:217]
	v_exp_f32_e32 v219, v219
	s_nop 0
	v_pk_add_f32 v[252:253], v[252:253], v[218:219]
	v_cvt_pk_bf16_f32 v208, v212, v213
	v_cvt_pk_bf16_f32 v209, v214, v215
	v_cvt_pk_bf16_f32 v210, v216, v217
	v_cvt_pk_bf16_f32 v211, v218, v219
	v_exp_f32_e32 v220, v220
	v_exp_f32_e32 v221, v221
	v_exp_f32_e32 v222, v222
	v_pk_add_f32 v[252:253], v[252:253], v[220:221]
	v_exp_f32_e32 v223, v223
	v_exp_f32_e32 v224, v224
	v_pk_add_f32 v[252:253], v[252:253], v[222:223]
	v_exp_f32_e32 v225, v225
	v_exp_f32_e32 v226, v226
	v_pk_add_f32 v[252:253], v[252:253], v[224:225]
	v_exp_f32_e32 v227, v227
	s_nop 0
	v_pk_add_f32 v[252:253], v[252:253], v[226:227]
	v_cvt_pk_bf16_f32 v212, v220, v221
	v_cvt_pk_bf16_f32 v213, v222, v223
	v_cvt_pk_bf16_f32 v214, v224, v225
	v_cvt_pk_bf16_f32 v215, v226, v227
	v_exp_f32_e32 v228, v228
	v_exp_f32_e32 v229, v229
	v_exp_f32_e32 v230, v230
	v_pk_add_f32 v[252:253], v[252:253], v[228:229]
	v_exp_f32_e32 v231, v231
	v_exp_f32_e32 v232, v232
	v_pk_add_f32 v[252:253], v[252:253], v[230:231]
	v_exp_f32_e32 v233, v233
	v_exp_f32_e32 v234, v234
	v_pk_add_f32 v[252:253], v[252:253], v[232:233]
	v_exp_f32_e32 v235, v235
	s_nop 0
	v_pk_add_f32 v[252:253], v[252:253], v[234:235]
	v_cvt_pk_bf16_f32 v216, v228, v229
	v_cvt_pk_bf16_f32 v217, v230, v231
	v_cvt_pk_bf16_f32 v218, v232, v233
	v_cvt_pk_bf16_f32 v219, v234, v235
	v_add_f32_e32 v252, v252, v253
	v_add_f32_e32 v196, v196, v252
	s_waitcnt lgkmcnt(5)
	v_mfma_f32_32x32x16_bf16 v[16:31], v[152:155], v[204:207], v[16:31]
	ds_read_b128 v[244:247], v197 offset:96
	s_waitcnt lgkmcnt(5)
	v_mfma_f32_32x32x16_bf16 v[0:15], v[156:159], v[204:207], v[0:15]
	ds_read_b128 v[248:251], v197 offset:4704
	s_waitcnt lgkmcnt(5)
	v_mfma_f32_32x32x16_bf16 v[16:31], v[160:163], v[208:211], v[16:31]
	s_waitcnt lgkmcnt(4)
	v_mfma_f32_32x32x16_bf16 v[0:15], v[164:167], v[208:211], v[0:15]
	s_waitcnt lgkmcnt(3)
	v_mfma_f32_32x32x16_bf16 v[16:31], v[236:239], v[212:215], v[16:31]
	s_waitcnt lgkmcnt(2)
	v_mfma_f32_32x32x16_bf16 v[0:15], v[240:243], v[212:215], v[0:15]
	s_waitcnt lgkmcnt(1)
	v_mfma_f32_32x32x16_bf16 v[16:31], v[244:247], v[216:219], v[16:31]
	s_waitcnt lgkmcnt(0)
	v_mfma_f32_32x32x16_bf16 v[0:15], v[248:251], v[216:219], v[0:15]
	s_branch .LBB0_1701
